# v18 plus spatial gating: first four W A-fragments loaded at the top of each group iteration instead of on demand between MFMAs
# speedup vs baseline: 1.0083x; 1.0058x over previous
; #define LAS __attribute__((address_space(3)))
; __device__ __forceinline__ unsigned cvtpk(float lo, float hi) { f32x2 v = {lo, hi}; bf16x2_t b = __builtin_convertvector(v, bf16x2_t); return __builtin_bit_cast(unsigned, b); }
; __device__ __forceinline__ float bflo(unsigned w) { return __uint_as_float(w << 16); }
; __device__ __forceinline__ float bfhi(unsigned w) { return __uint_as_float(w & 0xffff0000u); }
; __device__ __forceinline__ void spatial_unit(LAS unsigned char* lds, const Args& a, int b, int n, int ghalf, int tid, int wid, int lane) {
;     ...
;     for (int gi = 0; gi < 4; ++gi) {
;         const int g = ghalf * 4 + gi;
;         { const int lc = tid & 31, ch = g * 256 + lc * 8, row0 = tid >> 5;
;           u32x4 w[8];
; #pragma unroll
;           for (int it = 0; it < 8; ++it) w[it] = *(const u32x4*)(VSp + (size_t)(tok0 + row0 + it * 16) * DM + ch);
;           const f32x4 g0 = *(const f32x4*)(a.sg_ln_g + ch), g1 = *(const f32x4*)(a.sg_ln_g + ch + 4), b0 = *(const f32x4*)(a.sg_ln_b + ch), b1 = *(const f32x4*)(a.sg_ln_b + ch + 4);
; #pragma unroll
;           for (int it = 0; it < 8; ++it) { const int row = row0 + it * 16; const f32x2 st = stats[row];
;             u32x4 o;
;             o.x = cvtpk((bflo(w[it].x) - st.x) * st.y * g0[0] + b0[0], (bfhi(w[it].x) - st.x) * st.y * g0[1] + b0[1]);
;             o.y = cvtpk((bflo(w[it].y) - st.x) * st.y * g0[2] + b0[2], (bfhi(w[it].y) - st.x) * st.y * g0[3] + b0[3]);
;             o.z = cvtpk((bflo(w[it].z) - st.x) * st.y * g1[0] + b1[0], (bfhi(w[it].z) - st.x) * st.y * g1[1] + b1[1]);
;             o.w = cvtpk((bflo(w[it].w) - st.x) * st.y * g1[2] + b1[2], (bfhi(w[it].w) - st.x) * st.y * g1[3] + b1[3]);
;             *(LAS u32x4*)(lds + row * 512 + ((lc ^ ((row & 3) << 2)) << 4)) = o; } }
;         __syncthreads();
;         f32x16 acc[4];
; #pragma unroll
;         for (int d = 0; d < 4; ++d)
; #pragma unroll
;             for (int i = 0; i < 16; ++i) acc[d][i] = 0.f;
;         const bf16_t* wrow = Wb + (size_t)g * 16384 + (size_t)(ib * 32 + r) * 128 + 8 * h;
;         bf16x8 afr[8];
; #pragma unroll
;         for (int ks = 0; ks < 8; ++ks) afr[ks] = *(const bf16x8*)(wrow + 16 * ks);
.LBB0_520:
	global_load_dwordx4 v[220:223], v[72:73], off offset:-128
	global_load_dwordx4 v[224:227], v[72:73], off offset:-96
	global_load_dwordx4 v[228:231], v[72:73], off offset:-64
	global_load_dwordx4 v[232:235], v[72:73], off offset:-32
	global_load_dwordx4 v[0:3], v[90:91], off
	global_load_dwordx4 v[8:11], v[90:91], off offset:-16
	global_load_dwordx4 v[4:7], v[92:93], off
	global_load_dwordx4 v[12:15], v[92:93], off offset:-16
	v_lshl_add_u64 v[18:19], v[74:75], 0, s[0:1]
	v_lshl_add_u64 v[20:21], v[76:77], 0, s[0:1]
	v_lshl_add_u64 v[22:23], v[78:79], 0, s[0:1]
	v_lshl_add_u64 v[24:25], v[80:81], 0, s[0:1]
	v_lshl_add_u64 v[26:27], v[82:83], 0, s[0:1]
	v_lshl_add_u64 v[28:29], v[84:85], 0, s[0:1]
	v_lshl_add_u64 v[30:31], v[86:87], 0, s[0:1]
	v_lshl_add_u64 v[32:33], v[88:89], 0, s[0:1]
	ds_read_b64 v[16:17], v145
	global_load_dwordx4 v[34:37], v[18:19], off
	s_nop 0
	global_load_dwordx4 v[18:21], v[20:21], off
	s_nop 0
	global_load_dwordx4 v[38:41], v[22:23], off
	s_nop 0
	global_load_dwordx4 v[22:25], v[24:25], off
	s_nop 0
	global_load_dwordx4 v[42:45], v[26:27], off
	s_nop 0
	global_load_dwordx4 v[26:29], v[28:29], off
	s_nop 0
	global_load_dwordx4 v[46:49], v[30:31], off
	s_nop 0
	global_load_dwordx4 v[30:33], v[32:33], off
	v_add_u32_e32 v165, v154, v153
	v_lshl_add_u64 v[104:105], v[94:95], 0, s[0:1]
	v_lshl_add_u64 v[102:103], v[96:97], 0, s[0:1]
	v_lshl_add_u64 v[100:101], v[68:69], 0, s[0:1]
	v_lshl_add_u64 v[108:109], v[98:99], 0, s[0:1]
	v_lshl_add_u64 v[106:107], v[70:71], 0, s[0:1]
	v_lshl_add_u64 v[110:111], v[66:67], 0, s[0:1]
	s_add_u32 s0, s0, 0x200
	s_addc_u32 s1, s1, 0
	v_lshl_add_u64 v[90:91], v[90:91], 0, s[60:61]
	v_lshl_add_u64 v[92:93], v[92:93], 0, s[60:61]
	s_cmpk_lg_i32 s0, 0x800
	s_waitcnt vmcnt(7)
	v_lshlrev_b32_e32 v50, 16, v34
	v_and_b32_e32 v51, 0xffff0000, v34
	v_lshlrev_b32_e32 v34, 16, v35
	v_and_b32_e32 v35, 0xffff0000, v35
	v_lshlrev_b32_e32 v52, 16, v36
	v_and_b32_e32 v53, 0xffff0000, v36
	v_lshlrev_b32_e32 v36, 16, v37
	v_and_b32_e32 v37, 0xffff0000, v37
	s_waitcnt vmcnt(6)
	v_lshlrev_b32_e32 v54, 16, v18
	v_and_b32_e32 v55, 0xffff0000, v18
	v_lshlrev_b32_e32 v56, 16, v19
	v_and_b32_e32 v57, 0xffff0000, v19
	s_waitcnt lgkmcnt(0)
	v_pk_add_f32 v[18:19], v[50:51], v[16:17] op_sel_hi:[1,0] neg_lo:[0,1] neg_hi:[0,1]
	v_pk_add_f32 v[34:35], v[34:35], v[16:17] op_sel_hi:[1,0] neg_lo:[0,1] neg_hi:[0,1]
	v_pk_add_f32 v[50:51], v[52:53], v[16:17] op_sel_hi:[1,0] neg_lo:[0,1] neg_hi:[0,1]
	v_pk_add_f32 v[36:37], v[36:37], v[16:17] op_sel_hi:[1,0] neg_lo:[0,1] neg_hi:[0,1]
	v_pk_mul_f32 v[18:19], v[16:17], v[18:19] op_sel:[1,0]
	v_pk_mul_f32 v[34:35], v[16:17], v[34:35] op_sel:[1,0]
	v_pk_mul_f32 v[50:51], v[16:17], v[50:51] op_sel:[1,0]
	v_pk_mul_f32 v[16:17], v[16:17], v[36:37] op_sel:[1,0]
	v_pk_fma_f32 v[18:19], v[8:9], v[18:19], v[12:13]
	v_pk_fma_f32 v[34:35], v[10:11], v[34:35], v[14:15]
	v_pk_fma_f32 v[36:37], v[0:1], v[50:51], v[4:5]
	v_pk_fma_f32 v[50:51], v[2:3], v[16:17], v[6:7]
	v_cvt_pk_bf16_f32 v16, v18, v19
	v_cvt_pk_bf16_f32 v17, v34, v35
	v_cvt_pk_bf16_f32 v18, v36, v37
	v_cvt_pk_bf16_f32 v19, v50, v51
	ds_write_b128 v64, v[16:19]
	ds_read_b64 v[16:17], v146
	v_lshlrev_b32_e32 v58, 16, v20
	v_and_b32_e32 v59, 0xffff0000, v20
	v_lshlrev_b32_e32 v20, 16, v21
	v_and_b32_e32 v21, 0xffff0000, v21
	s_waitcnt lgkmcnt(0)
	v_pk_add_f32 v[18:19], v[54:55], v[16:17] op_sel_hi:[1,0] neg_lo:[0,1] neg_hi:[0,1]
	v_pk_add_f32 v[34:35], v[56:57], v[16:17] op_sel_hi:[1,0] neg_lo:[0,1] neg_hi:[0,1]
	v_pk_add_f32 v[36:37], v[58:59], v[16:17] op_sel_hi:[1,0] neg_lo:[0,1] neg_hi:[0,1]
	v_pk_add_f32 v[20:21], v[20:21], v[16:17] op_sel_hi:[1,0] neg_lo:[0,1] neg_hi:[0,1]
	v_pk_mul_f32 v[18:19], v[16:17], v[18:19] op_sel:[1,0]
	v_pk_mul_f32 v[34:35], v[16:17], v[34:35] op_sel:[1,0]
	v_pk_mul_f32 v[36:37], v[16:17], v[36:37] op_sel:[1,0]
	v_pk_mul_f32 v[16:17], v[16:17], v[20:21] op_sel:[1,0]
	v_pk_fma_f32 v[18:19], v[8:9], v[18:19], v[12:13]
	v_pk_fma_f32 v[20:21], v[10:11], v[34:35], v[14:15]
	v_pk_fma_f32 v[34:35], v[0:1], v[36:37], v[4:5]
	v_pk_fma_f32 v[36:37], v[2:3], v[16:17], v[6:7]
	v_cvt_pk_bf16_f32 v16, v18, v19
	v_cvt_pk_bf16_f32 v17, v20, v21
	v_cvt_pk_bf16_f32 v18, v34, v35
	v_cvt_pk_bf16_f32 v19, v36, v37
	ds_write_b128 v155, v[16:19]
	ds_read_b64 v[16:17], v147
	s_waitcnt vmcnt(5)
	v_lshlrev_b32_e32 v60, 16, v38
	v_and_b32_e32 v61, 0xffff0000, v38
	v_lshlrev_b32_e32 v38, 16, v39
	v_and_b32_e32 v39, 0xffff0000, v39
	v_lshlrev_b32_e32 v62, 16, v40
	v_and_b32_e32 v63, 0xffff0000, v40
	v_lshlrev_b32_e32 v40, 16, v41
	v_and_b32_e32 v41, 0xffff0000, v41
	s_waitcnt lgkmcnt(0)
	v_pk_add_f32 v[18:19], v[60:61], v[16:17] op_sel_hi:[1,0] neg_lo:[0,1] neg_hi:[0,1]
	v_pk_add_f32 v[20:21], v[38:39], v[16:17] op_sel_hi:[1,0] neg_lo:[0,1] neg_hi:[0,1]
	v_pk_add_f32 v[34:35], v[62:63], v[16:17] op_sel_hi:[1,0] neg_lo:[0,1] neg_hi:[0,1]
	v_pk_add_f32 v[36:37], v[40:41], v[16:17] op_sel_hi:[1,0] neg_lo:[0,1] neg_hi:[0,1]
	v_pk_mul_f32 v[18:19], v[16:17], v[18:19] op_sel:[1,0]
	v_pk_mul_f32 v[20:21], v[16:17], v[20:21] op_sel:[1,0]
	v_pk_mul_f32 v[34:35], v[16:17], v[34:35] op_sel:[1,0]
	v_pk_mul_f32 v[16:17], v[16:17], v[36:37] op_sel:[1,0]
	v_pk_fma_f32 v[18:19], v[8:9], v[18:19], v[12:13]
	v_pk_fma_f32 v[20:21], v[10:11], v[20:21], v[14:15]
	v_pk_fma_f32 v[34:35], v[0:1], v[34:35], v[4:5]
	v_pk_fma_f32 v[36:37], v[2:3], v[16:17], v[6:7]
	v_cvt_pk_bf16_f32 v16, v18, v19
	v_cvt_pk_bf16_f32 v17, v20, v21
	v_cvt_pk_bf16_f32 v18, v34, v35
	v_cvt_pk_bf16_f32 v19, v36, v37
	ds_write_b128 v156, v[16:19]
	ds_read_b64 v[16:17], v148
	s_waitcnt vmcnt(4)
; #define LAS __attribute__((address_space(3)))
; __device__ __forceinline__ unsigned cvtpk(float lo, float hi) { f32x2 v = {lo, hi}; bf16x2_t b = __builtin_convertvector(v, bf16x2_t); return __builtin_bit_cast(unsigned, b); }
; __device__ __forceinline__ float bflo(unsigned w) { return __uint_as_float(w << 16); }
; __device__ __forceinline__ float bfhi(unsigned w) { return __uint_as_float(w & 0xffff0000u); }
; __device__ __forceinline__ void spatial_unit(LAS unsigned char* lds, const Args& a, int b, int n, int ghalf, int tid, int wid, int lane) {
;     ...
;         { const int lc = tid & 31, ch = g * 256 + lc * 8, row0 = tid >> 5;
;           u32x4 w[8];
; #pragma unroll
;           for (int it = 0; it < 8; ++it) w[it] = *(const u32x4*)(VSp + (size_t)(tok0 + row0 + it * 16) * DM + ch);
;           const f32x4 g0 = *(const f32x4*)(a.sg_ln_g + ch), g1 = *(const f32x4*)(a.sg_ln_g + ch + 4), b0 = *(const f32x4*)(a.sg_ln_b + ch), b1 = *(const f32x4*)(a.sg_ln_b + ch + 4);
; #pragma unroll
;           for (int it = 0; it < 8; ++it) { const int row = row0 + it * 16; const f32x2 st = stats[row];
;             u32x4 o;
;             o.x = cvtpk((bflo(w[it].x) - st.x) * st.y * g0[0] + b0[0], (bfhi(w[it].x) - st.x) * st.y * g0[1] + b0[1]);
;             o.y = cvtpk((bflo(w[it].y) - st.x) * st.y * g0[2] + b0[2], (bfhi(w[it].y) - st.x) * st.y * g0[3] + b0[3]);
;             o.z = cvtpk((bflo(w[it].z) - st.x) * st.y * g1[0] + b1[0], (bfhi(w[it].z) - st.x) * st.y * g1[1] + b1[1]);
;             o.w = cvtpk((bflo(w[it].w) - st.x) * st.y * g1[2] + b1[2], (bfhi(w[it].w) - st.x) * st.y * g1[3] + b1[3]);
;             *(LAS u32x4*)(lds + row * 512 + ((lc ^ ((row & 3) << 2)) << 4)) = o; } }
;         __syncthreads();
	v_lshlrev_b32_e32 v112, 16, v22
	v_and_b32_e32 v113, 0xffff0000, v22
	v_lshlrev_b32_e32 v22, 16, v23
	v_and_b32_e32 v23, 0xffff0000, v23
	v_lshlrev_b32_e32 v114, 16, v24
	v_and_b32_e32 v115, 0xffff0000, v24
	v_lshlrev_b32_e32 v24, 16, v25
	v_and_b32_e32 v25, 0xffff0000, v25
	s_waitcnt lgkmcnt(0)
	v_pk_add_f32 v[18:19], v[112:113], v[16:17] op_sel_hi:[1,0] neg_lo:[0,1] neg_hi:[0,1]
	v_pk_add_f32 v[20:21], v[22:23], v[16:17] op_sel_hi:[1,0] neg_lo:[0,1] neg_hi:[0,1]
	v_pk_add_f32 v[22:23], v[114:115], v[16:17] op_sel_hi:[1,0] neg_lo:[0,1] neg_hi:[0,1]
	v_pk_add_f32 v[24:25], v[24:25], v[16:17] op_sel_hi:[1,0] neg_lo:[0,1] neg_hi:[0,1]
	v_pk_mul_f32 v[18:19], v[16:17], v[18:19] op_sel:[1,0]
	v_pk_mul_f32 v[20:21], v[16:17], v[20:21] op_sel:[1,0]
	v_pk_mul_f32 v[22:23], v[16:17], v[22:23] op_sel:[1,0]
	v_pk_mul_f32 v[16:17], v[16:17], v[24:25] op_sel:[1,0]
	v_pk_fma_f32 v[18:19], v[8:9], v[18:19], v[12:13]
	v_pk_fma_f32 v[20:21], v[10:11], v[20:21], v[14:15]
	v_pk_fma_f32 v[22:23], v[0:1], v[22:23], v[4:5]
	v_pk_fma_f32 v[24:25], v[2:3], v[16:17], v[6:7]
	v_cvt_pk_bf16_f32 v16, v18, v19
	v_cvt_pk_bf16_f32 v17, v20, v21
	v_cvt_pk_bf16_f32 v18, v22, v23
	v_cvt_pk_bf16_f32 v19, v24, v25
	ds_write_b128 v157, v[16:19]
	ds_read_b64 v[16:17], v149
	s_waitcnt vmcnt(3)
	v_lshlrev_b32_e32 v116, 16, v42
	v_and_b32_e32 v117, 0xffff0000, v42
	v_lshlrev_b32_e32 v42, 16, v43
	v_and_b32_e32 v43, 0xffff0000, v43
	v_lshlrev_b32_e32 v118, 16, v44
	v_and_b32_e32 v119, 0xffff0000, v44
	v_lshlrev_b32_e32 v44, 16, v45
	v_and_b32_e32 v45, 0xffff0000, v45
	s_waitcnt lgkmcnt(0)
	v_pk_add_f32 v[18:19], v[116:117], v[16:17] op_sel_hi:[1,0] neg_lo:[0,1] neg_hi:[0,1]
	v_pk_add_f32 v[20:21], v[42:43], v[16:17] op_sel_hi:[1,0] neg_lo:[0,1] neg_hi:[0,1]
	v_pk_add_f32 v[22:23], v[118:119], v[16:17] op_sel_hi:[1,0] neg_lo:[0,1] neg_hi:[0,1]
	v_pk_add_f32 v[24:25], v[44:45], v[16:17] op_sel_hi:[1,0] neg_lo:[0,1] neg_hi:[0,1]
	v_pk_mul_f32 v[18:19], v[16:17], v[18:19] op_sel:[1,0]
	v_pk_mul_f32 v[20:21], v[16:17], v[20:21] op_sel:[1,0]
	v_pk_mul_f32 v[22:23], v[16:17], v[22:23] op_sel:[1,0]
	v_pk_mul_f32 v[16:17], v[16:17], v[24:25] op_sel:[1,0]
	v_pk_fma_f32 v[18:19], v[8:9], v[18:19], v[12:13]
	v_pk_fma_f32 v[20:21], v[10:11], v[20:21], v[14:15]
	v_pk_fma_f32 v[22:23], v[0:1], v[22:23], v[4:5]
	v_pk_fma_f32 v[24:25], v[2:3], v[16:17], v[6:7]
	v_cvt_pk_bf16_f32 v16, v18, v19
	v_cvt_pk_bf16_f32 v17, v20, v21
	v_cvt_pk_bf16_f32 v18, v22, v23
	v_cvt_pk_bf16_f32 v19, v24, v25
	ds_write_b128 v158, v[16:19]
	ds_read_b64 v[16:17], v150
	s_waitcnt vmcnt(2)
	v_lshlrev_b32_e32 v120, 16, v26
	v_and_b32_e32 v121, 0xffff0000, v26
	v_lshlrev_b32_e32 v26, 16, v27
	v_and_b32_e32 v27, 0xffff0000, v27
	v_lshlrev_b32_e32 v122, 16, v28
	v_and_b32_e32 v123, 0xffff0000, v28
	v_lshlrev_b32_e32 v28, 16, v29
	v_and_b32_e32 v29, 0xffff0000, v29
	s_waitcnt lgkmcnt(0)
	v_pk_add_f32 v[18:19], v[120:121], v[16:17] op_sel_hi:[1,0] neg_lo:[0,1] neg_hi:[0,1]
	v_pk_add_f32 v[20:21], v[26:27], v[16:17] op_sel_hi:[1,0] neg_lo:[0,1] neg_hi:[0,1]
	v_pk_add_f32 v[22:23], v[122:123], v[16:17] op_sel_hi:[1,0] neg_lo:[0,1] neg_hi:[0,1]
	v_pk_add_f32 v[24:25], v[28:29], v[16:17] op_sel_hi:[1,0] neg_lo:[0,1] neg_hi:[0,1]
	v_pk_mul_f32 v[18:19], v[16:17], v[18:19] op_sel:[1,0]
	v_pk_mul_f32 v[20:21], v[16:17], v[20:21] op_sel:[1,0]
	v_pk_mul_f32 v[22:23], v[16:17], v[22:23] op_sel:[1,0]
	v_pk_mul_f32 v[16:17], v[16:17], v[24:25] op_sel:[1,0]
	v_pk_fma_f32 v[18:19], v[8:9], v[18:19], v[12:13]
	v_pk_fma_f32 v[20:21], v[10:11], v[20:21], v[14:15]
	v_pk_fma_f32 v[22:23], v[0:1], v[22:23], v[4:5]
	v_pk_fma_f32 v[24:25], v[2:3], v[16:17], v[6:7]
	v_cvt_pk_bf16_f32 v16, v18, v19
	v_cvt_pk_bf16_f32 v17, v20, v21
	v_cvt_pk_bf16_f32 v18, v22, v23
	v_cvt_pk_bf16_f32 v19, v24, v25
	ds_write_b128 v159, v[16:19]
	ds_read_b64 v[16:17], v151
	s_waitcnt vmcnt(1)
	v_lshlrev_b32_e32 v124, 16, v46
	v_and_b32_e32 v125, 0xffff0000, v46
	v_lshlrev_b32_e32 v46, 16, v47
	v_and_b32_e32 v47, 0xffff0000, v47
	v_lshlrev_b32_e32 v126, 16, v48
	v_and_b32_e32 v127, 0xffff0000, v48
	v_lshlrev_b32_e32 v48, 16, v49
	v_and_b32_e32 v49, 0xffff0000, v49
	s_waitcnt lgkmcnt(0)
	v_pk_add_f32 v[18:19], v[124:125], v[16:17] op_sel_hi:[1,0] neg_lo:[0,1] neg_hi:[0,1]
	v_pk_add_f32 v[20:21], v[46:47], v[16:17] op_sel_hi:[1,0] neg_lo:[0,1] neg_hi:[0,1]
	v_pk_add_f32 v[22:23], v[126:127], v[16:17] op_sel_hi:[1,0] neg_lo:[0,1] neg_hi:[0,1]
	v_pk_add_f32 v[24:25], v[48:49], v[16:17] op_sel_hi:[1,0] neg_lo:[0,1] neg_hi:[0,1]
	v_pk_mul_f32 v[18:19], v[16:17], v[18:19] op_sel:[1,0]
	v_pk_mul_f32 v[20:21], v[16:17], v[20:21] op_sel:[1,0]
	v_pk_mul_f32 v[22:23], v[16:17], v[22:23] op_sel:[1,0]
	v_pk_mul_f32 v[16:17], v[16:17], v[24:25] op_sel:[1,0]
	v_pk_fma_f32 v[18:19], v[8:9], v[18:19], v[12:13]
	v_pk_fma_f32 v[20:21], v[10:11], v[20:21], v[14:15]
	v_pk_fma_f32 v[22:23], v[0:1], v[22:23], v[4:5]
	v_pk_fma_f32 v[24:25], v[2:3], v[16:17], v[6:7]
	v_cvt_pk_bf16_f32 v16, v18, v19
	v_cvt_pk_bf16_f32 v17, v20, v21
	v_cvt_pk_bf16_f32 v18, v22, v23
	v_cvt_pk_bf16_f32 v19, v24, v25
	ds_write_b128 v160, v[16:19]
	ds_read_b64 v[16:17], v152
	s_waitcnt vmcnt(0)
	v_lshlrev_b32_e32 v128, 16, v30
	v_and_b32_e32 v129, 0xffff0000, v30
	v_lshlrev_b32_e32 v30, 16, v31
	v_and_b32_e32 v31, 0xffff0000, v31
	v_lshlrev_b32_e32 v130, 16, v32
	v_and_b32_e32 v131, 0xffff0000, v32
	v_lshlrev_b32_e32 v32, 16, v33
	v_and_b32_e32 v33, 0xffff0000, v33
	s_waitcnt lgkmcnt(0)
	v_pk_add_f32 v[18:19], v[128:129], v[16:17] op_sel_hi:[1,0] neg_lo:[0,1] neg_hi:[0,1]
	v_pk_add_f32 v[20:21], v[30:31], v[16:17] op_sel_hi:[1,0] neg_lo:[0,1] neg_hi:[0,1]
	v_pk_add_f32 v[22:23], v[130:131], v[16:17] op_sel_hi:[1,0] neg_lo:[0,1] neg_hi:[0,1]
	v_pk_add_f32 v[24:25], v[32:33], v[16:17] op_sel_hi:[1,0] neg_lo:[0,1] neg_hi:[0,1]
	v_pk_mul_f32 v[18:19], v[16:17], v[18:19] op_sel:[1,0]
	v_pk_mul_f32 v[20:21], v[16:17], v[20:21] op_sel:[1,0]
	v_pk_mul_f32 v[22:23], v[16:17], v[22:23] op_sel:[1,0]
	v_pk_mul_f32 v[16:17], v[16:17], v[24:25] op_sel:[1,0]
	v_pk_fma_f32 v[8:9], v[8:9], v[18:19], v[12:13]
	v_pk_fma_f32 v[10:11], v[10:11], v[20:21], v[14:15]
	v_pk_fma_f32 v[4:5], v[0:1], v[22:23], v[4:5]
	v_pk_fma_f32 v[6:7], v[2:3], v[16:17], v[6:7]
	v_cvt_pk_bf16_f32 v0, v8, v9
	v_cvt_pk_bf16_f32 v1, v10, v11
	v_cvt_pk_bf16_f32 v2, v4, v5
	v_cvt_pk_bf16_f32 v3, v6, v7
	ds_write_b128 v161, v[0:3]
	s_waitcnt lgkmcnt(0)
	s_barrier
; #define LAS __attribute__((address_space(3)))
; __device__ __forceinline__ s16x4 vtr(const LAS unsigned char* p) { return __builtin_bit_cast(s16x4, __builtin_amdgcn_ds_read_tr16_b64_v4i16((LAS v4i16_t*)p)); }
; #define MFMA32(a, b, c) __builtin_amdgcn_mfma_f32_32x32x16_bf16((a), (b), (c), 0, 0, 0)
; __device__ __forceinline__ void spatial_unit(LAS unsigned char* lds, const Args& a, int b, int n, int ghalf, int tid, int wid, int lane) {
;     ...
;         const bf16_t* wrow = Wb + (size_t)g * 16384 + (size_t)(ib * 32 + r) * 128 + 8 * h;
;         bf16x8 afr[8];
; #pragma unroll
;         for (int ks = 0; ks < 8; ++ks) afr[ks] = *(const bf16x8*)(wrow + 16 * ks);
; #pragma unroll
;         for (int ks = 0; ks < 8; ++ks) {
;             const bf16x8 af = afr[ks];
;             const LAS unsigned char* vb = lds + (16 * ks + 8 * h + tq) * 512 + (2 * g16 + (tp >> 1)) * 16 + (tp & 1) * 8;
; #pragma unroll
;             for (int d = 0; d < 4; ++d) { const int db = dbh * 4 + d;
;                 const LAS unsigned char* vp = vb + (((db ^ tq) & 3) << 6) + (db >> 2) * 256;
;                 const s16x4 lo = vtr(vp), hi = vtr(vp + 4 * 512);
;                 const bf16x8 bfr = __builtin_shufflevector(lo, hi, 0, 1, 2, 3, 4, 5, 6, 7);
;                 acc[d] = MFMA32(af, bfr, acc[d]); }
;         }
	s_nop 0
	s_nop 0
	ds_read_b64_tr_b16 v[0:1], v165
	ds_read_b64_tr_b16 v[2:3], v165 offset:2048
	ds_read_b64_tr_b16 v[118:119], v165 offset:8192
	ds_read_b64_tr_b16 v[120:121], v165 offset:10240
	s_waitcnt vmcnt(1) lgkmcnt(2)
	v_mfma_f32_32x32x16_bf16 v[0:15], v[220:223], v[0:3], 0
	ds_read_b64_tr_b16 v[16:17], v162
	ds_read_b64_tr_b16 v[18:19], v162 offset:2048
	ds_read_b64_tr_b16 v[122:123], v162 offset:8192
	ds_read_b64_tr_b16 v[124:125], v162 offset:10240
	ds_read_b64_tr_b16 v[32:33], v163
	ds_read_b64_tr_b16 v[34:35], v163 offset:2048
	ds_read_b64_tr_b16 v[166:167], v163 offset:8192
	ds_read_b64_tr_b16 v[168:169], v163 offset:10240
	ds_read_b64_tr_b16 v[52:53], v164
	ds_read_b64_tr_b16 v[54:55], v164 offset:2048
	ds_read_b64_tr_b16 v[170:171], v164 offset:8192
	ds_read_b64_tr_b16 v[172:173], v164 offset:10240
	v_add_co_u32_e32 v128, vcc, s57, v104
	s_nop 1
	v_addc_co_u32_e32 v129, vcc, 0, v105, vcc
	s_waitcnt lgkmcnt(6)
	v_mfma_f32_32x32x16_bf16 v[32:47], v[220:223], v[32:35], 0
	v_add_co_u32_e32 v134, vcc, s64, v104
	s_nop 1
	v_addc_co_u32_e32 v135, vcc, 0, v105, vcc
	v_add_co_u32_e32 v132, vcc, s35, v104
	s_waitcnt vmcnt(0)
	v_mfma_f32_32x32x16_bf16 v[0:15], v[224:227], v[118:121], v[0:15]
	s_nop 0
	v_addc_co_u32_e32 v133, vcc, 0, v105, vcc
	v_add_co_u32_e32 v130, vcc, s57, v102
	s_nop 1
	v_addc_co_u32_e32 v131, vcc, 0, v103, vcc
	s_waitcnt lgkmcnt(4)
	v_mfma_f32_32x32x16_bf16 v[32:47], v[224:227], v[166:169], v[32:47]
	s_nop 0
	v_add_co_u32_e32 v126, vcc, s64, v102
	s_nop 1
	v_addc_co_u32_e32 v127, vcc, 0, v103, vcc
	v_mfma_f32_32x32x16_bf16 v[16:31], v[220:223], v[16:19], 0
	s_waitcnt lgkmcnt(2)
	v_mfma_f32_32x32x16_bf16 v[48:63], v[220:223], v[52:55], 0
	v_mfma_f32_32x32x16_bf16 v[16:31], v[224:227], v[122:125], v[16:31]
	v_add_co_u32_e32 v124, vcc, s35, v102
	s_nop 1
	v_addc_co_u32_e32 v125, vcc, 0, v103, vcc
	v_add_co_u32_e32 v112, vcc, s57, v108
	s_waitcnt lgkmcnt(0)
	v_mfma_f32_32x32x16_bf16 v[48:63], v[224:227], v[170:173], v[48:63]
	ds_read_b64_tr_b16 v[114:115], v165 offset:16384
	ds_read_b64_tr_b16 v[116:117], v165 offset:18432
	ds_read_b64_tr_b16 v[170:171], v165 offset:24576
	ds_read_b64_tr_b16 v[172:173], v165 offset:26624
	ds_read_b64_tr_b16 v[178:179], v162 offset:16384
	ds_read_b64_tr_b16 v[180:181], v162 offset:18432
	ds_read_b64_tr_b16 v[182:183], v162 offset:24576
	ds_read_b64_tr_b16 v[184:185], v162 offset:26624
	v_addc_co_u32_e32 v113, vcc, 0, v109, vcc
	s_waitcnt vmcnt(1) lgkmcnt(6)
	v_mfma_f32_32x32x16_bf16 v[0:15], v[228:231], v[114:117], v[0:15]
	v_add_co_u32_e32 v114, vcc, s64, v108
	s_nop 1
	v_addc_co_u32_e32 v115, vcc, 0, v109, vcc
	v_add_co_u32_e32 v122, vcc, s35, v108
	s_waitcnt lgkmcnt(2)
	v_mfma_f32_32x32x16_bf16 v[16:31], v[228:231], v[178:181], v[16:31]
	ds_read_b64_tr_b16 v[178:179], v163 offset:16384
	ds_read_b64_tr_b16 v[180:181], v163 offset:18432
	ds_read_b64_tr_b16 v[186:187], v163 offset:24576
	ds_read_b64_tr_b16 v[188:189], v163 offset:26624
	v_addc_co_u32_e32 v123, vcc, 0, v109, vcc
	s_waitcnt lgkmcnt(2)
	v_mfma_f32_32x32x16_bf16 v[32:47], v[228:231], v[178:181], v[32:47]
	ds_read_b64_tr_b16 v[178:179], v164 offset:16384
	ds_read_b64_tr_b16 v[180:181], v164 offset:18432
	ds_read_b64_tr_b16 v[190:191], v164 offset:24576
	ds_read_b64_tr_b16 v[192:193], v164 offset:26624
	s_waitcnt vmcnt(0)
	v_mfma_f32_32x32x16_bf16 v[0:15], v[232:235], v[170:173], v[0:15]
	global_load_dwordx4 v[170:173], v[72:73], off
	s_waitcnt lgkmcnt(2)
	v_mfma_f32_32x32x16_bf16 v[48:63], v[228:231], v[178:181], v[48:63]
	global_load_dwordx4 v[178:181], v[72:73], off offset:32
	v_add_co_u32_e32 v120, vcc, s57, v106
	s_nop 1
	v_addc_co_u32_e32 v121, vcc, 0, v107, vcc
	v_add_co_u32_e32 v118, vcc, s64, v106
	v_mfma_f32_32x32x16_bf16 v[16:31], v[232:235], v[182:185], v[16:31]
	s_nop 0
	v_addc_co_u32_e32 v119, vcc, 0, v107, vcc
	v_add_co_u32_e32 v116, vcc, s35, v106
	s_nop 1
	v_addc_co_u32_e32 v117, vcc, 0, v107, vcc
	v_mfma_f32_32x32x16_bf16 v[32:47], v[232:235], v[186:189], v[32:47]
	s_waitcnt lgkmcnt(0)
	v_mfma_f32_32x32x16_bf16 v[48:63], v[232:235], v[190:193], v[48:63]
	global_load_dwordx4 v[166:169], v[72:73], off offset:64
	ds_read_b64_tr_b16 v[182:183], v165 offset:32768
	ds_read_b64_tr_b16 v[184:185], v165 offset:34816
	ds_read_b64_tr_b16 v[186:187], v165 offset:40960
	ds_read_b64_tr_b16 v[188:189], v165 offset:43008
	s_waitcnt vmcnt(2) lgkmcnt(2)
	v_mfma_f32_32x32x16_bf16 v[0:15], v[170:173], v[182:185], v[0:15]
	global_load_dwordx4 v[182:185], v[72:73], off offset:96
	ds_read_b64_tr_b16 v[190:191], v162 offset:32768
	ds_read_b64_tr_b16 v[192:193], v162 offset:34816
	ds_read_b64_tr_b16 v[194:195], v163 offset:32768
	ds_read_b64_tr_b16 v[196:197], v163 offset:34816
	ds_read_b64_tr_b16 v[200:201], v162 offset:40960
	ds_read_b64_tr_b16 v[202:203], v162 offset:43008
	v_lshl_add_u64 v[72:73], v[72:73], 0, s[58:59]
	s_waitcnt lgkmcnt(4)
; #define LAS __attribute__((address_space(3)))
; __device__ __forceinline__ s16x4 vtr(const LAS unsigned char* p) { return __builtin_bit_cast(s16x4, __builtin_amdgcn_ds_read_tr16_b64_v4i16((LAS v4i16_t*)p)); }
; #define MFMA32(a, b, c) __builtin_amdgcn_mfma_f32_32x32x16_bf16((a), (b), (c), 0, 0, 0)
; __device__ __forceinline__ void spatial_unit(LAS unsigned char* lds, const Args& a, int b, int n, int ghalf, int tid, int wid, int lane) {
;     ...
;         for (int ks = 0; ks < 8; ++ks) afr[ks] = *(const bf16x8*)(wrow + 16 * ks);
; #pragma unroll
;         for (int ks = 0; ks < 8; ++ks) {
;             const bf16x8 af = afr[ks];
;             const LAS unsigned char* vb = lds + (16 * ks + 8 * h + tq) * 512 + (2 * g16 + (tp >> 1)) * 16 + (tp & 1) * 8;
; #pragma unroll
;             for (int d = 0; d < 4; ++d) { const int db = dbh * 4 + d;
;                 const LAS unsigned char* vp = vb + (((db ^ tq) & 3) << 6) + (db >> 2) * 256;
;                 const s16x4 lo = vtr(vp), hi = vtr(vp + 4 * 512);
;                 const bf16x8 bfr = __builtin_shufflevector(lo, hi, 0, 1, 2, 3, 4, 5, 6, 7);
;                 acc[d] = MFMA32(af, bfr, acc[d]); }
;         }
; #pragma unroll
;         for (int hh2 = 0; hh2 < 2; ++hh2) {
;             bf16_t uv[8][4]; float bias[8];
; #pragma unroll
;             for (int ii = 0; ii < 8; ++ii) { const int i = hh2 * 8 + ii, il = ib * 32 + (i & 3) + 8 * (i >> 2) + 4 * h; bias[ii] = a.sg_b[g * 128 + il];
;                 const size_t off = (size_t)(tok0 + il) * DM + g * 256 + dbh * 128 + r;
; #pragma unroll
;                 for (int d = 0; d < 4; ++d) uv[ii][d] = Up[off + 32 * d]; }
	v_mfma_f32_32x32x16_bf16 v[16:31], v[170:173], v[190:193], v[16:31]
	ds_read_b64_tr_b16 v[190:191], v163 offset:40960
	ds_read_b64_tr_b16 v[192:193], v163 offset:43008
	ds_read_b64_tr_b16 v[204:205], v164 offset:32768
	ds_read_b64_tr_b16 v[206:207], v164 offset:34816
	ds_read_b64_tr_b16 v[208:209], v164 offset:40960
	ds_read_b64_tr_b16 v[210:211], v164 offset:43008
	global_load_ushort v174, v[104:105], off
	global_load_ushort v175, v[104:105], off offset:64
	global_load_ushort v199, v[104:105], off offset:128
	global_load_ushort v212, v[104:105], off offset:192
	global_load_ushort v213, v[134:135], off offset:-4096
	global_load_ushort v214, v[128:129], off offset:64
	global_load_ushort v215, v[128:129], off offset:128
	global_load_ushort v216, v[128:129], off offset:192
	global_load_ushort v217, v[134:135], off
	global_load_ushort v218, v[134:135], off offset:64
	global_load_ushort v219, v[134:135], off offset:128
	global_load_ushort v220, v[134:135], off offset:192
	global_load_ushort v221, v[132:133], off
	global_load_ushort v222, v[132:133], off offset:64
	global_load_ushort v223, v[132:133], off offset:128
	global_load_ushort v224, v[132:133], off offset:192
	global_load_ushort v225, v[102:103], off
	global_load_ushort v226, v[102:103], off offset:64
	global_load_ushort v227, v[102:103], off offset:128
	global_load_ushort v228, v[102:103], off offset:192
	global_load_ushort v229, v[126:127], off offset:-4096
	global_load_ushort v230, v[130:131], off offset:64
	global_load_ushort v231, v[130:131], off offset:128
	global_load_ushort v232, v[130:131], off offset:192
	global_load_ushort v233, v[126:127], off
	global_load_ushort v234, v[126:127], off offset:64
	global_load_ushort v235, v[126:127], off offset:128
	global_load_ushort v236, v[126:127], off offset:192
	global_load_ushort v237, v[124:125], off
	global_load_ushort v238, v[124:125], off offset:64
	global_load_ushort v239, v[124:125], off offset:128
	global_load_ushort v240, v[124:125], off offset:192
	s_waitcnt lgkmcnt(8)
	v_mfma_f32_32x32x16_bf16 v[32:47], v[170:173], v[194:197], v[32:47]
	s_waitcnt lgkmcnt(2)
	v_mfma_f32_32x32x16_bf16 v[48:63], v[170:173], v[204:207], v[48:63]
	global_load_dwordx4 v[170:173], v[100:101], off
	s_waitcnt vmcnt(35)
	v_mfma_f32_32x32x16_bf16 v[0:15], v[178:181], v[186:189], v[0:15]
	v_mfma_f32_32x32x16_bf16 v[16:31], v[178:181], v[200:203], v[16:31]
	v_mfma_f32_32x32x16_bf16 v[32:47], v[178:181], v[190:193], v[32:47]
	s_waitcnt lgkmcnt(0)
	v_mfma_f32_32x32x16_bf16 v[48:63], v[178:181], v[208:211], v[48:63]
	ds_read_b64_tr_b16 v[178:179], v165 offset:49152
	ds_read_b64_tr_b16 v[180:181], v165 offset:51200
	ds_read_b64_tr_b16 v[186:187], v165 offset:57344
	ds_read_b64_tr_b16 v[188:189], v165 offset:59392
	s_waitcnt vmcnt(32)
	v_lshlrev_b32_e32 v165, 16, v174
	s_waitcnt lgkmcnt(2)
	v_mfma_f32_32x32x16_bf16 v[0:15], v[166:169], v[178:181], v[0:15]
	global_load_dwordx4 v[178:181], v[100:101], off offset:32
	ds_read_b64_tr_b16 v[190:191], v162 offset:49152
	ds_read_b64_tr_b16 v[192:193], v162 offset:51200
	ds_read_b64_tr_b16 v[194:195], v162 offset:57344
	ds_read_b64_tr_b16 v[196:197], v162 offset:59392
	s_waitcnt vmcnt(32)
	v_lshlrev_b32_e32 v174, 16, v175
	s_waitcnt vmcnt(31)
	v_lshlrev_b32_e32 v175, 16, v199
	s_waitcnt vmcnt(18)
	v_lshlrev_b32_e32 v199, 16, v224
	s_waitcnt lgkmcnt(2)
	v_mfma_f32_32x32x16_bf16 v[16:31], v[166:169], v[190:193], v[16:31]
	ds_read_b64_tr_b16 v[190:191], v163 offset:49152
	ds_read_b64_tr_b16 v[192:193], v163 offset:51200
	ds_read_b64_tr_b16 v[200:201], v163 offset:57344
	ds_read_b64_tr_b16 v[202:203], v163 offset:59392
	ds_read_b64_tr_b16 v[204:205], v164 offset:49152
	ds_read_b64_tr_b16 v[206:207], v164 offset:51200
	ds_read_b64_tr_b16 v[208:209], v164 offset:57344
	ds_read_b64_tr_b16 v[210:211], v164 offset:59392
	s_waitcnt lgkmcnt(6)
	v_mfma_f32_32x32x16_bf16 v[32:47], v[166:169], v[190:193], v[32:47]
	v_lshlrev_b32_e32 v190, 16, v212
	v_lshlrev_b32_e32 v191, 16, v217
	v_lshlrev_b32_e32 v192, 16, v218
	v_lshlrev_b32_e32 v193, 16, v219
	s_waitcnt vmcnt(9)
	v_lshlrev_b32_e32 v212, 16, v233
	s_waitcnt lgkmcnt(2)
	v_mfma_f32_32x32x16_bf16 v[48:63], v[166:169], v[204:207], v[48:63]
	v_lshlrev_b32_e32 v166, 16, v213
	v_lshlrev_b32_e32 v167, 16, v214
	v_lshlrev_b32_e32 v168, 16, v215
	v_lshlrev_b32_e32 v169, 16, v216
	v_lshlrev_b32_e32 v204, 16, v225
	v_lshlrev_b32_e32 v205, 16, v226
	v_lshlrev_b32_e32 v206, 16, v231
	v_mfma_f32_32x32x16_bf16 v[0:15], v[182:185], v[186:189], v[0:15]
	v_lshlrev_b32_e32 v186, 16, v220
	v_lshlrev_b32_e32 v187, 16, v221
	v_lshlrev_b32_e32 v188, 16, v222
	v_lshlrev_b32_e32 v189, 16, v223
	v_lshlrev_b32_e32 v207, 16, v232
	s_waitcnt vmcnt(4)
	v_lshlrev_b32_e32 v213, 16, v238
	s_waitcnt vmcnt(3)
	v_lshlrev_b32_e32 v214, 16, v239
	v_mfma_f32_32x32x16_bf16 v[16:31], v[182:185], v[194:197], v[16:31]
	s_waitcnt vmcnt(1)
	s_nop 0
	v_add_f32_e32 v0, v0, v170
	v_lshlrev_b32_e32 v194, 16, v227
	v_lshlrev_b32_e32 v195, 16, v228
	v_lshlrev_b32_e32 v196, 16, v229
	v_lshlrev_b32_e32 v197, 16, v230
	v_lshlrev_b32_e32 v215, 16, v240
	v_add_f32_e32 v1, v1, v171
	v_mfma_f32_32x32x16_bf16 v[32:47], v[182:185], v[200:203], v[32:47]
	v_lshlrev_b32_e32 v200, 16, v234
	v_lshlrev_b32_e32 v201, 16, v235
	v_lshlrev_b32_e32 v202, 16, v236
	v_lshlrev_b32_e32 v203, 16, v237
	v_add_f32_e32 v16, v16, v170
	v_add_f32_e32 v17, v17, v171
	v_add_f32_e32 v2, v2, v172
	s_waitcnt lgkmcnt(0)
; __device__ __forceinline__ unsigned cvtpk(float lo, float hi) { f32x2 v = {lo, hi}; bf16x2_t b = __builtin_convertvector(v, bf16x2_t); return __builtin_bit_cast(unsigned, b); }
; __device__ __forceinline__ float bf2f(bf16_t b) { return __uint_as_float(((unsigned)b) << 16); }
; __device__ __forceinline__ void spatial_unit(LAS unsigned char* lds, const Args& a, int b, int n, int ghalf, int tid, int wid, int lane) {
;     ...
; #pragma unroll
;         for (int hh2 = 0; hh2 < 2; ++hh2) {
;             bf16_t uv[8][4]; float bias[8];
; #pragma unroll
;             for (int ii = 0; ii < 8; ++ii) { const int i = hh2 * 8 + ii, il = ib * 32 + (i & 3) + 8 * (i >> 2) + 4 * h; bias[ii] = a.sg_b[g * 128 + il];
;                 const size_t off = (size_t)(tok0 + il) * DM + g * 256 + dbh * 128 + r;
; #pragma unroll
;                 for (int d = 0; d < 4; ++d) uv[ii][d] = Up[off + 32 * d]; }
;             asm volatile("" ::: "memory");
; #pragma unroll
;             for (int ii = 0; ii < 8; ++ii) { const int i = hh2 * 8 + ii, il = ib * 32 + (i & 3) + 8 * (i >> 2) + 4 * h;
;                 const size_t off = (size_t)(tok0 + il) * DM + g * 256 + dbh * 128 + r;
; #pragma unroll
;                 for (int d = 0; d < 4; ++d) Up[off + 32 * d] = (bf16_t)(cvtpk(bf2f(uv[ii][d]) * (acc[d][i] + bias[ii]), 0.f) & 0xffffu); }
	v_mfma_f32_32x32x16_bf16 v[48:63], v[182:185], v[208:211], v[48:63]
	s_nop 2
	v_add_f32_e32 v32, v32, v170
	v_add_f32_e32 v33, v33, v171
	v_add_f32_e32 v18, v18, v172
	v_add_f32_e32 v34, v34, v172
	v_add_f32_e32 v3, v3, v173
	v_add_f32_e32 v19, v19, v173
	v_add_f32_e32 v35, v35, v173
	s_nop 1
	v_add_f32_e32 v48, v48, v170
	v_add_f32_e32 v49, v49, v171
	v_add_f32_e32 v50, v50, v172
	v_add_f32_e32 v51, v51, v173
	v_mul_f32_e32 v0, v0, v165
	v_mul_f32_e32 v16, v16, v174
	v_mul_f32_e32 v32, v32, v175
	v_mul_f32_e32 v48, v48, v190
	v_mul_f32_e32 v1, v1, v166
	v_mul_f32_e32 v17, v17, v167
	v_mul_f32_e32 v33, v33, v168
	v_mul_f32_e32 v49, v49, v169
	v_mul_f32_e32 v2, v2, v191
	v_mul_f32_e32 v18, v18, v192
	v_mul_f32_e32 v34, v34, v193
	v_mul_f32_e32 v50, v50, v186
	v_mul_f32_e32 v3, v3, v187
	s_waitcnt vmcnt(0)
	v_add_f32_e32 v4, v4, v178
	v_add_f32_e32 v20, v20, v178
	v_add_f32_e32 v36, v36, v178
	v_add_f32_e32 v52, v52, v178
	v_add_f32_e32 v5, v5, v179
	v_add_f32_e32 v21, v21, v179
	v_add_f32_e32 v37, v37, v179
	v_add_f32_e32 v53, v53, v179
	v_add_f32_e32 v6, v6, v180
	v_add_f32_e32 v22, v22, v180
	v_add_f32_e32 v38, v38, v180
	v_add_f32_e32 v54, v54, v180
	v_add_f32_e32 v7, v7, v181
	v_add_f32_e32 v23, v23, v181
	v_add_f32_e32 v39, v39, v181
	v_add_f32_e32 v55, v55, v181
	v_mul_f32_e32 v19, v19, v188
	v_mul_f32_e32 v35, v35, v189
	v_mul_f32_e32 v51, v51, v199
	v_mul_f32_e32 v4, v4, v204
	v_mul_f32_e32 v20, v20, v205
	v_mul_f32_e32 v36, v36, v194
	v_mul_f32_e32 v52, v52, v195
	v_mul_f32_e32 v5, v5, v196
	v_mul_f32_e32 v21, v21, v197
	v_mul_f32_e32 v37, v37, v206
	v_mul_f32_e32 v53, v53, v207
	v_mul_f32_e32 v6, v6, v212
	v_mul_f32_e32 v22, v22, v200
	v_mul_f32_e32 v38, v38, v201
	v_mul_f32_e32 v54, v54, v202
	v_mul_f32_e32 v7, v7, v203
	v_mul_f32_e32 v23, v23, v213
	v_mul_f32_e32 v39, v39, v214
	v_mul_f32_e32 v55, v55, v215
	v_cvt_pk_bf16_f32 v0, v0, s0
	v_cvt_pk_bf16_f32 v16, v16, s0
	v_cvt_pk_bf16_f32 v32, v32, s0
	v_cvt_pk_bf16_f32 v48, v48, s0
	v_cvt_pk_bf16_f32 v1, v1, s0
	v_cvt_pk_bf16_f32 v17, v17, s0
	v_cvt_pk_bf16_f32 v33, v33, s0
	v_cvt_pk_bf16_f32 v49, v49, s0
	v_cvt_pk_bf16_f32 v2, v2, s0
	v_cvt_pk_bf16_f32 v18, v18, s0
	v_cvt_pk_bf16_f32 v34, v34, s0
	v_cvt_pk_bf16_f32 v50, v50, s0
	v_cvt_pk_bf16_f32 v3, v3, s0
	v_cvt_pk_bf16_f32 v19, v19, s0
	v_cvt_pk_bf16_f32 v35, v35, s0
	v_cvt_pk_bf16_f32 v51, v51, s0
	v_cvt_pk_bf16_f32 v4, v4, s0
	v_cvt_pk_bf16_f32 v20, v20, s0
	v_cvt_pk_bf16_f32 v36, v36, s0
	v_cvt_pk_bf16_f32 v52, v52, s0
	v_cvt_pk_bf16_f32 v5, v5, s0
	v_cvt_pk_bf16_f32 v21, v21, s0
	v_cvt_pk_bf16_f32 v37, v37, s0
	v_cvt_pk_bf16_f32 v53, v53, s0
	v_cvt_pk_bf16_f32 v6, v6, s0
	v_cvt_pk_bf16_f32 v22, v22, s0
	v_cvt_pk_bf16_f32 v38, v38, s0
	v_cvt_pk_bf16_f32 v54, v54, s0
	v_cvt_pk_bf16_f32 v7, v7, s0
	v_cvt_pk_bf16_f32 v23, v23, s0
	v_cvt_pk_bf16_f32 v39, v39, s0
	v_cvt_pk_bf16_f32 v55, v55, s0
	global_store_short v[104:105], v0, off
	global_store_short v[104:105], v16, off offset:64
	global_store_short v[104:105], v32, off offset:128
	global_store_short v[104:105], v48, off offset:192
	global_store_short v[134:135], v1, off offset:-4096
	global_store_short v[128:129], v17, off offset:64
	global_store_short v[128:129], v33, off offset:128
	global_store_short v[128:129], v49, off offset:192
	global_store_short v[134:135], v2, off
	global_store_short v[134:135], v18, off offset:64
	global_store_short v[134:135], v34, off offset:128
	global_store_short v[134:135], v50, off offset:192
	global_store_short v[132:133], v3, off
	global_store_short v[132:133], v19, off offset:64
	global_store_short v[132:133], v35, off offset:128
	global_store_short v[132:133], v51, off offset:192
	global_store_short v[102:103], v4, off
	global_store_short v[102:103], v20, off offset:64
	global_store_short v[102:103], v36, off offset:128
	global_store_short v[102:103], v52, off offset:192
	global_store_short v[126:127], v5, off offset:-4096
	global_store_short v[130:131], v21, off offset:64
	global_store_short v[130:131], v37, off offset:128
	global_store_short v[130:131], v53, off offset:192
	global_store_short v[126:127], v6, off
	global_store_short v[126:127], v22, off offset:64
	global_store_short v[126:127], v38, off offset:128
	global_store_short v[126:127], v54, off offset:192
	global_store_short v[124:125], v7, off
	global_store_short v[124:125], v23, off offset:64
	global_store_short v[124:125], v39, off offset:128
	global_store_short v[124:125], v55, off offset:192
	global_load_ushort v7, v[108:109], off
	global_load_dword v16, v[100:101], off offset:64
	global_load_ushort v17, v[108:109], off offset:64
	global_load_ushort v18, v[108:109], off offset:128
	global_load_ushort v19, v[108:109], off offset:192
	global_load_ushort v20, v[114:115], off offset:-4096
	global_load_dwordx3 v[4:6], v[110:111], off offset:68
	global_load_ushort v21, v[112:113], off offset:64
	global_load_ushort v22, v[112:113], off offset:128
	global_load_ushort v23, v[112:113], off offset:192
	global_load_ushort v32, v[114:115], off
	global_load_ushort v33, v[114:115], off offset:64
	global_load_ushort v34, v[114:115], off offset:128
	global_load_ushort v35, v[114:115], off offset:192
	global_load_ushort v36, v[122:123], off
	global_load_ushort v37, v[122:123], off offset:64
	global_load_ushort v38, v[122:123], off offset:128
	global_load_ushort v39, v[122:123], off offset:192
	global_load_ushort v48, v[106:107], off
	global_load_dwordx4 v[0:3], v[100:101], off offset:96
	global_load_ushort v49, v[106:107], off offset:64
	global_load_ushort v50, v[106:107], off offset:128
	global_load_ushort v51, v[106:107], off offset:192
	global_load_ushort v52, v[118:119], off offset:-4096
	global_load_ushort v53, v[120:121], off offset:64
	global_load_ushort v54, v[120:121], off offset:128
	global_load_ushort v55, v[120:121], off offset:192
	global_load_ushort v100, v[118:119], off
	global_load_ushort v101, v[118:119], off offset:64
	global_load_ushort v102, v[118:119], off offset:128
	global_load_ushort v103, v[118:119], off offset:192
	global_load_ushort v104, v[116:117], off
	global_load_ushort v105, v[116:117], off offset:64
	global_load_ushort v110, v[116:117], off offset:128
	global_load_ushort v111, v[116:117], off offset:192
	s_waitcnt vmcnt(34)
; __device__ __forceinline__ unsigned cvtpk(float lo, float hi) { f32x2 v = {lo, hi}; bf16x2_t b = __builtin_convertvector(v, bf16x2_t); return __builtin_bit_cast(unsigned, b); }
; __device__ __forceinline__ float bf2f(bf16_t b) { return __uint_as_float(((unsigned)b) << 16); }
; __device__ __forceinline__ void spatial_unit(LAS unsigned char* lds, const Args& a, int b, int n, int ghalf, int tid, int wid, int lane) {
;     ...
; #pragma unroll
;         for (int hh2 = 0; hh2 < 2; ++hh2) {
;             bf16_t uv[8][4]; float bias[8];
; #pragma unroll
;             for (int ii = 0; ii < 8; ++ii) { const int i = hh2 * 8 + ii, il = ib * 32 + (i & 3) + 8 * (i >> 2) + 4 * h; bias[ii] = a.sg_b[g * 128 + il];
;                 const size_t off = (size_t)(tok0 + il) * DM + g * 256 + dbh * 128 + r;
; #pragma unroll
;                 for (int d = 0; d < 4; ++d) uv[ii][d] = Up[off + 32 * d]; }
;             asm volatile("" ::: "memory");
; #pragma unroll
;             for (int ii = 0; ii < 8; ++ii) { const int i = hh2 * 8 + ii, il = ib * 32 + (i & 3) + 8 * (i >> 2) + 4 * h;
;                 const size_t off = (size_t)(tok0 + il) * DM + g * 256 + dbh * 128 + r;
; #pragma unroll
;                 for (int d = 0; d < 4; ++d) Up[off + 32 * d] = (bf16_t)(cvtpk(bf2f(uv[ii][d]) * (acc[d][i] + bias[ii]), 0.f) & 0xffffu); }
;             asm volatile("" ::: "memory");
;         }
;         __syncthreads();
;     }
	v_lshlrev_b32_e32 v7, 16, v7
	s_waitcnt vmcnt(33)
	v_add_f32_e32 v8, v8, v16
	s_waitcnt vmcnt(32)
	v_lshlrev_b32_e32 v17, 16, v17
	v_add_f32_e32 v24, v24, v16
	s_waitcnt vmcnt(31)
	v_lshlrev_b32_e32 v18, 16, v18
	v_add_f32_e32 v40, v40, v16
	s_waitcnt vmcnt(30)
	v_lshlrev_b32_e32 v19, 16, v19
	v_add_f32_e32 v16, v56, v16
	s_waitcnt vmcnt(29)
	v_lshlrev_b32_e32 v20, 16, v20
	s_waitcnt vmcnt(28)
	v_add_f32_e32 v9, v9, v4
	s_waitcnt vmcnt(27)
	v_lshlrev_b32_e32 v21, 16, v21
	v_add_f32_e32 v25, v25, v4
	s_waitcnt vmcnt(26)
	v_lshlrev_b32_e32 v22, 16, v22
	v_add_f32_e32 v41, v41, v4
	s_waitcnt vmcnt(25)
	v_lshlrev_b32_e32 v23, 16, v23
	v_add_f32_e32 v4, v57, v4
	s_waitcnt vmcnt(24)
	v_lshlrev_b32_e32 v32, 16, v32
	v_add_f32_e32 v10, v10, v5
	s_waitcnt vmcnt(23)
	v_lshlrev_b32_e32 v33, 16, v33
	v_add_f32_e32 v26, v26, v5
	s_waitcnt vmcnt(22)
	v_lshlrev_b32_e32 v34, 16, v34
	v_add_f32_e32 v42, v42, v5
	s_waitcnt vmcnt(21)
	v_lshlrev_b32_e32 v35, 16, v35
	v_add_f32_e32 v5, v58, v5
	s_waitcnt vmcnt(20)
	v_lshlrev_b32_e32 v36, 16, v36
	v_add_f32_e32 v11, v11, v6
	s_waitcnt vmcnt(19)
	v_lshlrev_b32_e32 v37, 16, v37
	v_add_f32_e32 v27, v27, v6
	s_waitcnt vmcnt(18)
	v_lshlrev_b32_e32 v38, 16, v38
	v_add_f32_e32 v43, v43, v6
	s_waitcnt vmcnt(17)
	v_lshlrev_b32_e32 v39, 16, v39
	v_add_f32_e32 v6, v59, v6
	s_waitcnt vmcnt(16)
	v_lshlrev_b32_e32 v48, 16, v48
	s_waitcnt vmcnt(15)
	v_add_f32_e32 v12, v12, v0
	s_waitcnt vmcnt(14)
	v_lshlrev_b32_e32 v49, 16, v49
	v_add_f32_e32 v28, v28, v0
	s_waitcnt vmcnt(13)
	v_lshlrev_b32_e32 v50, 16, v50
	v_add_f32_e32 v44, v44, v0
	s_waitcnt vmcnt(12)
	v_lshlrev_b32_e32 v51, 16, v51
	v_add_f32_e32 v0, v60, v0
	s_waitcnt vmcnt(11)
	v_lshlrev_b32_e32 v52, 16, v52
	v_add_f32_e32 v13, v13, v1
	s_waitcnt vmcnt(10)
	v_lshlrev_b32_e32 v53, 16, v53
	v_add_f32_e32 v29, v29, v1
	s_waitcnt vmcnt(9)
	v_lshlrev_b32_e32 v54, 16, v54
	v_add_f32_e32 v45, v45, v1
	s_waitcnt vmcnt(8)
	v_lshlrev_b32_e32 v55, 16, v55
	v_add_f32_e32 v1, v61, v1
	s_waitcnt vmcnt(7)
	v_lshlrev_b32_e32 v56, 16, v100
	v_add_f32_e32 v14, v14, v2
	s_waitcnt vmcnt(6)
	v_lshlrev_b32_e32 v57, 16, v101
	v_add_f32_e32 v30, v30, v2
	s_waitcnt vmcnt(5)
	v_lshlrev_b32_e32 v58, 16, v102
	v_add_f32_e32 v46, v46, v2
	s_waitcnt vmcnt(4)
	v_lshlrev_b32_e32 v59, 16, v103
	v_add_f32_e32 v2, v62, v2
	s_waitcnt vmcnt(3)
	v_lshlrev_b32_e32 v60, 16, v104
	v_add_f32_e32 v15, v15, v3
	s_waitcnt vmcnt(2)
	v_lshlrev_b32_e32 v61, 16, v105
	v_add_f32_e32 v31, v31, v3
	s_waitcnt vmcnt(1)
	v_lshlrev_b32_e32 v62, 16, v110
	v_add_f32_e32 v47, v47, v3
	s_waitcnt vmcnt(0)
	v_lshlrev_b32_e32 v100, 16, v111
	v_add_f32_e32 v3, v63, v3
	v_mul_f32_e32 v7, v8, v7
	v_mul_f32_e32 v8, v24, v17
	v_mul_f32_e32 v17, v40, v18
	v_mul_f32_e32 v16, v16, v19
	v_mul_f32_e32 v9, v9, v20
	v_mul_f32_e32 v18, v25, v21
	v_mul_f32_e32 v19, v41, v22
	v_mul_f32_e32 v4, v4, v23
	v_mul_f32_e32 v10, v10, v32
	v_mul_f32_e32 v20, v26, v33
	v_mul_f32_e32 v21, v42, v34
	v_mul_f32_e32 v5, v5, v35
	v_mul_f32_e32 v11, v11, v36
	v_mul_f32_e32 v22, v27, v37
	v_mul_f32_e32 v23, v43, v38
	v_mul_f32_e32 v6, v6, v39
	v_mul_f32_e32 v12, v12, v48
	v_mul_f32_e32 v24, v28, v49
	v_mul_f32_e32 v25, v44, v50
	v_mul_f32_e32 v0, v0, v51
	v_mul_f32_e32 v13, v13, v52
	v_mul_f32_e32 v26, v29, v53
	v_mul_f32_e32 v27, v45, v54
	v_mul_f32_e32 v1, v1, v55
	v_mul_f32_e32 v14, v14, v56
	v_mul_f32_e32 v28, v30, v57
	v_mul_f32_e32 v29, v46, v58
	v_mul_f32_e32 v2, v2, v59
	v_mul_f32_e32 v15, v15, v60
	v_mul_f32_e32 v30, v31, v61
	v_mul_f32_e32 v31, v47, v62
	v_mul_f32_e32 v3, v3, v100
	v_cvt_pk_bf16_f32 v7, v7, s0
	v_cvt_pk_bf16_f32 v8, v8, s0
	v_cvt_pk_bf16_f32 v17, v17, s0
	v_cvt_pk_bf16_f32 v16, v16, s0
	v_cvt_pk_bf16_f32 v9, v9, s0
	v_cvt_pk_bf16_f32 v18, v18, s0
	v_cvt_pk_bf16_f32 v19, v19, s0
	v_cvt_pk_bf16_f32 v4, v4, s0
	v_cvt_pk_bf16_f32 v10, v10, s0
	v_cvt_pk_bf16_f32 v20, v20, s0
	v_cvt_pk_bf16_f32 v21, v21, s0
	v_cvt_pk_bf16_f32 v5, v5, s0
	v_cvt_pk_bf16_f32 v11, v11, s0
	v_cvt_pk_bf16_f32 v22, v22, s0
	v_cvt_pk_bf16_f32 v23, v23, s0
	v_cvt_pk_bf16_f32 v6, v6, s0
	v_cvt_pk_bf16_f32 v12, v12, s0
	v_cvt_pk_bf16_f32 v24, v24, s0
	v_cvt_pk_bf16_f32 v25, v25, s0
	v_cvt_pk_bf16_f32 v0, v0, s0
	v_cvt_pk_bf16_f32 v13, v13, s0
	v_cvt_pk_bf16_f32 v26, v26, s0
	v_cvt_pk_bf16_f32 v27, v27, s0
	v_cvt_pk_bf16_f32 v1, v1, s0
	v_cvt_pk_bf16_f32 v14, v14, s0
	v_cvt_pk_bf16_f32 v28, v28, s0
	v_cvt_pk_bf16_f32 v29, v29, s0
	v_cvt_pk_bf16_f32 v2, v2, s0
	v_cvt_pk_bf16_f32 v15, v15, s0
	v_cvt_pk_bf16_f32 v30, v30, s0
	v_cvt_pk_bf16_f32 v31, v31, s0
	v_cvt_pk_bf16_f32 v3, v3, s0
	global_store_short v[108:109], v7, off
	global_store_short v[108:109], v8, off offset:64
	global_store_short v[108:109], v17, off offset:128
	global_store_short v[108:109], v16, off offset:192
	global_store_short v[114:115], v9, off offset:-4096
	global_store_short v[112:113], v18, off offset:64
	global_store_short v[112:113], v19, off offset:128
	global_store_short v[112:113], v4, off offset:192
	global_store_short v[114:115], v10, off
	global_store_short v[114:115], v20, off offset:64
	global_store_short v[114:115], v21, off offset:128
	global_store_short v[114:115], v5, off offset:192
	global_store_short v[122:123], v11, off
	global_store_short v[122:123], v22, off offset:64
	global_store_short v[122:123], v23, off offset:128
	global_store_short v[122:123], v6, off offset:192
	global_store_short v[106:107], v12, off
	global_store_short v[106:107], v24, off offset:64
	global_store_short v[106:107], v25, off offset:128
	global_store_short v[106:107], v0, off offset:192
	global_store_short v[118:119], v13, off offset:-4096
	global_store_short v[120:121], v26, off offset:64
	global_store_short v[120:121], v27, off offset:128
	global_store_short v[120:121], v1, off offset:192
	global_store_short v[118:119], v14, off
	global_store_short v[118:119], v28, off offset:64
	global_store_short v[118:119], v29, off offset:128
	global_store_short v[118:119], v2, off offset:192
	global_store_short v[116:117], v15, off
	global_store_short v[116:117], v30, off offset:64
	global_store_short v[116:117], v31, off offset:128
	global_store_short v[116:117], v3, off offset:192
	s_barrier
	s_cbranch_scc1 .LBB0_520
	s_add_i32 s65, s65, s30
	s_add_i32 s15, s15, s22
	s_add_i32 s23, s23, s33
	s_cmpk_gt_i32 s65, 0xff
	s_cbranch_scc0 .LBB0_509
